# P4: item order remapped so 8 consecutive workgroups take the 8 heads of the same chunk (contiguous 2KB per row), consecutive chunks per workgroup
# baseline (speedup 1.0000x reference)
.LBB0_563:
	v_readlane_b32 s0, v255, 4
	s_cmp_lt_i32 s0, 5
	v_readlane_b32 s1, v255, 5
	s_cselect_b64 s[44:45], -1, 0
	s_and_b64 s[0:1], s[44:45], s[2:3]
	s_andn2_b64 vcc, exec, s[0:1]
	v_lshrrev_b32_e32 v129, 4, v128
	s_cbranch_vccnz .LBB0_614
	s_and_b32 s100, s33, 7
	s_lshl_b32 s100, s100, 8
	s_lshr_b32 s101, s33, 3
	s_lshl_b32 s101, s101, 3
	s_or_b32 s100, s100, s101
	s_cmpk_lt_i32 s100, 0x1000
	s_cselect_b64 s[4:5], -1, 0
	s_lshl_b32 s63, s100, 3
	s_add_u32 s50, s80, 0x3ed00000
	s_addc_u32 s51, s81, 0
	s_add_u32 s52, s80, 0x8000000
	s_addc_u32 s53, s81, 0
	s_add_u32 s0, s80, 0x3ef00000
	s_addc_u32 s1, s81, 0
	v_lshrrev_b32_e32 v49, 6, v128
	s_add_u32 s66, s80, 0x3f120000
	s_waitcnt vmcnt(0)
	v_add_u32_e32 v1, 0x1000, v98
	v_add_u32_e32 v2, 0x3000, v98
	v_lshrrev_b32_e32 v4, 2, v128
	s_addc_u32 s67, s81, 0
	v_and_b32_e32 v48, 0x78, v98
	v_add_u32_e32 v45, 0x200, v128
	v_and_b32_e32 v0, 0x1f80, v98
	v_and_b32_e32 v1, 0x3f80, v1
	v_and_b32_e32 v2, 0x7f80, v2
	v_and_b32_e32 v3, 0x7f, v128
	v_lshlrev_b32_e32 v50, 4, v49
	v_and_b32_e32 v4, 12, v4
	v_and_b32_e32 v110, 15, v128
	s_movk_i32 s9, 0x1000
	s_cmpk_gt_i32 s100, 0xfff
	v_cmp_gt_u32_e64 s[2:3], 64, v128
	v_mov_b32_e32 v85, 0
	v_lshrrev_b32_e32 v111, 4, v45
	s_movk_i32 s8, 0x3000
	v_lshlrev_b32_e32 v84, 2, v50
	v_lshlrev_b32_e32 v46, 2, v4
	v_lshlrev_b32_e32 v72, 1, v50
	v_lshlrev_b32_e32 v74, 1, v4
	v_lshlrev_b32_e32 v44, 2, v3
	v_lshlrev_b32_e32 v76, 1, v48
	v_lshlrev_b32_e32 v78, 1, v2
	v_lshlrev_b32_e32 v80, 1, v0
	v_lshlrev_b32_e32 v82, 1, v1
	s_cbranch_scc1 .LBB0_568
	s_and_b32 s18, s100, 0xff
	s_bfe_u32 s12, s100, 0x30008
	s_and_b32 s6, s63, 0xffffc000
	s_lshl_b32 s7, s18, 6
	s_or_b32 s13, s6, s7
	s_lshl_b32 s6, s12, 9
	s_add_u32 s10, s74, s6
	s_addc_u32 s11, s75, 0
	v_lshl_add_u64 v[0:1], s[10:11], 0, v[84:85]
	v_mov_b32_e32 v47, v85
	v_or_b32_e32 v4, s13, v110
	v_lshl_add_u64 v[52:53], v[0:1], 0, v[46:47]
	v_or_b32_e32 v2, 48, v4
	s_movk_i32 s19, 0x3800
	v_mov_b64_e32 v[0:1], s[52:53]
	s_mov_b32 s7, 0
	v_mad_i64_i32 v[2:3], s[10:11], v2, s19, v[0:1]
	s_lshl_b32 s6, s12, 8
	v_lshl_add_u64 v[2:3], v[2:3], 0, s[6:7]
	v_mov_b32_e32 v73, v85
	v_lshl_add_u64 v[2:3], v[2:3], 0, v[72:73]
	v_mov_b32_e32 v75, v85
	v_lshl_add_u64 v[24:25], v[2:3], 0, v[74:75]
	v_or_b32_e32 v2, 32, v4
	v_mad_i64_i32 v[2:3], s[10:11], v2, s19, v[0:1]
	v_lshl_add_u64 v[2:3], v[2:3], 0, s[6:7]
	v_lshl_add_u64 v[2:3], v[2:3], 0, v[72:73]
	v_lshl_add_u64 v[26:27], v[2:3], 0, v[74:75]
	v_or_b32_e32 v2, 16, v4
	v_mad_i64_i32 v[2:3], s[10:11], v2, s19, v[0:1]
	v_lshl_add_u64 v[2:3], v[2:3], 0, s[6:7]
	v_lshl_add_u64 v[2:3], v[2:3], 0, v[72:73]
	v_lshl_add_u64 v[54:55], v[2:3], 0, v[74:75]
	v_mad_i64_i32 v[2:3], s[10:11], v4, s19, v[0:1]
	s_cmp_lg_u32 s18, 0
	s_cselect_b64 s[10:11], -1, 0
	s_cmp_lg_u64 s[10:11], 0
	s_subb_u32 s10, s100, 0
	s_ashr_i32 s11, s10, 31
	s_lshl_b64 s[14:15], s[10:11], 2
	s_add_u32 s14, s66, s14
	s_addc_u32 s15, s67, s15
	s_lshl_b64 s[16:17], s[10:11], 9
	s_add_u32 s16, s0, s16
	s_addc_u32 s17, s1, s17
	s_lshl_b64 s[10:11], s[10:11], 15
	v_lshl_add_u64 v[2:3], v[2:3], 0, s[6:7]
	s_add_u32 s10, s78, s10
	v_lshl_add_u64 v[2:3], v[2:3], 0, v[72:73]
	s_addc_u32 s11, s79, s11
	v_mov_b32_e32 v77, v85
	v_lshl_add_u64 v[56:57], v[2:3], 0, v[74:75]
	v_lshl_add_u64 v[2:3], s[10:11], 0, v[76:77]
	v_mov_b32_e32 v79, v85
	v_mov_b32_e32 v81, v85
	v_mov_b32_e32 v83, v85
	v_lshl_add_u64 v[58:59], v[2:3], 0, v[78:79]
	v_lshl_add_u64 v[60:61], v[2:3], 0, v[80:81]
	v_lshl_add_u64 v[28:29], v[2:3], 0, v[82:83]
	v_add_u32_e32 v2, s13, v111
	v_mad_i64_i32 v[2:3], s[10:11], v2, s19, v[0:1]
	v_lshl_add_u64 v[2:3], v[2:3], 0, s[6:7]
	v_lshl_add_u64 v[16:17], v[2:3], 0, v[76:77]
	v_or_b32_e32 v2, s13, v129
	v_mad_i64_i32 v[0:1], s[10:11], v2, s19, v[0:1]
	v_lshl_add_u64 v[0:1], v[0:1], 0, s[6:7]
	v_lshl_add_u64 v[0:1], v[0:1], 0, v[76:77]
	v_add_co_u32_e32 v2, vcc, s9, v0
	s_movk_i32 s6, 0x2000
	s_nop 0
	v_addc_co_u32_e32 v3, vcc, 0, v1, vcc
	v_add_co_u32_e32 v8, vcc, s6, v0
	s_cmp_eq_u32 s18, 0
	s_nop 0
	v_addc_co_u32_e32 v9, vcc, 0, v1, vcc
	v_add_co_u32_e32 v12, vcc, s9, v16
	global_load_dwordx4 v[0:3], v[2:3], off offset:2048
	s_nop 0
	global_load_dwordx4 v[4:7], v[8:9], off
	v_addc_co_u32_e32 v13, vcc, 0, v17, vcc
	v_add_co_u32_e32 v30, vcc, s6, v16
	s_movk_i32 s6, 0x4000
	s_nop 0
	v_addc_co_u32_e32 v31, vcc, 0, v17, vcc
	global_load_dwordx4 v[8:11], v[8:9], off offset:2048
	s_nop 0
	global_load_dwordx4 v[12:15], v[12:13], off offset:2048
	s_nop 0
	global_load_dwordx4 v[16:19], v[30:31], off
	global_load_dwordx4 v[20:23], v[30:31], off offset:2048
	global_load_dwordx4 v[32:35], v[28:29], off
	v_add_co_u32_e32 v28, vcc, s6, v60
	v_mov_b32_e32 v73, 0
	s_nop 0
	v_addc_co_u32_e32 v29, vcc, 0, v61, vcc
	v_add_co_u32_e32 v56, vcc, s8, v56
	global_load_dwordx4 v[36:39], v[28:29], off
	s_nop 0
	global_load_dwordx4 v[28:31], v[60:61], off
	global_load_dwordx4 v[40:43], v[58:59], off
	global_load_dword v47, v44, s[16:17]
	global_load_dword v51, v85, s[14:15]
	v_addc_co_u32_e32 v57, vcc, 0, v57, vcc
	v_add_co_u32_e32 v54, vcc, s8, v54
	s_nop 1
	v_addc_co_u32_e32 v55, vcc, 0, v55, vcc
	v_add_co_u32_e32 v58, vcc, s8, v26
	s_cselect_b64 s[8:9], -1, 0
	s_nop 0
	v_addc_co_u32_e32 v59, vcc, 0, v27, vcc
	v_add_co_u32_e32 v60, vcc, 0x3000, v24
	s_waitcnt vmcnt(0)
	v_cndmask_b32_e64 v35, v35, 0, s[8:9]
	v_addc_co_u32_e32 v61, vcc, 0, v25, vcc
	global_load_dwordx2 v[100:101], v[56:57], off
	global_load_dwordx2 v[98:99], v[54:55], off
	global_load_dwordx2 v[90:91], v[58:59], off
	global_load_dwordx2 v[86:87], v[60:61], off
	global_load_dwordx4 v[24:27], v[52:53], off
	v_cndmask_b32_e64 v34, v34, 0, s[8:9]
	v_cndmask_b32_e64 v31, v31, 0, s[8:9]
	v_cndmask_b32_e64 v30, v30, 0, s[8:9]
	v_cndmask_b32_e64 v29, v29, 0, s[8:9]
	v_cndmask_b32_e64 v28, v28, 0, s[8:9]
	v_cndmask_b32_e64 v33, v33, 0, s[8:9]
	v_cndmask_b32_e64 v32, v32, 0, s[8:9]
	v_cndmask_b32_e64 v39, v39, 0, s[8:9]
	v_cndmask_b32_e64 v38, v38, 0, s[8:9]
	v_cndmask_b32_e64 v37, v37, 0, s[8:9]
	v_cndmask_b32_e64 v36, v36, 0, s[8:9]
	v_cndmask_b32_e64 v43, v43, 0, s[8:9]
	v_cndmask_b32_e64 v42, v42, 0, s[8:9]
	v_cndmask_b32_e64 v41, v41, 0, s[8:9]
	v_cndmask_b32_e64 v40, v40, 0, s[8:9]
	s_and_saveexec_b64 s[10:11], s[2:3]
	s_cbranch_execz .LBB0_567
	v_or_b32_e32 v52, s13, v128
	v_ashrrev_i32_e32 v53, 31, v52
	v_lshlrev_b64 v[52:53], 6, v[52:53]
	v_lshl_add_u64 v[52:53], s[50:51], 0, v[52:53]
	s_lshl_b32 s6, s12, 2
	v_lshl_add_u64 v[52:53], v[52:53], 0, s[6:7]
	global_load_dword v85, v[52:53], off
	global_load_dword v73, v[52:53], off offset:32

.LBB0_569:
	v_and_b32_e32 v47, 63, v128
	v_cmp_eq_u32_e64 s[4:5], 0, v47
	v_cmp_gt_u32_e64 s[6:7], 2, v47
	v_cmp_gt_u32_e64 s[8:9], 4, v47
	v_cmp_gt_u32_e64 s[10:11], 8, v47
	v_cmp_gt_u32_e64 s[12:13], 16, v47
	v_cmp_gt_u32_e64 s[14:15], 32, v47
	s_add_i32 s42, 16, 0x17c00
	v_lshlrev_b32_e32 v47, 2, v47
	s_add_i32 s18, 16, 0x17d00
	s_add_i32 s43, 16, 0x17e00
	s_add_i32 s54, 16, 0x17f00
	s_add_i32 s62, 16, 0x18000
	s_add_i32 s64, 16, 0x18200
	s_add_i32 s65, 16, 0x18300
	v_lshrrev_b32_e32 v45, 7, v45
	v_add_u32_e32 v112, s42, v47
	v_add_u32_e32 v113, s18, v47
	v_add_u32_e32 v114, s43, v47
	v_add_u32_e32 v115, s54, v47
	v_add_u32_e32 v116, s62, v47
	v_add_u32_e32 v117, s64, v47
	v_add_u32_e32 v118, s65, v47
	v_lshrrev_b32_e32 v47, 7, v128
	v_xor_b32_e32 v45, v45, v128
	v_lshl_add_u32 v52, v48, 1, 16
	v_lshl_or_b32 v53, v47, 4, v110
	v_and_b32_e32 v63, 7, v129
	v_mul_u32_u24_e32 v65, 0x88, v129
	v_mul_u32_u24_e32 v48, 0x48, v48
	v_lshlrev_b32_e32 v45, 3, v45
	v_lshlrev_b32_e32 v54, 2, v53
	v_and_b32_e32 v56, 48, v128
	v_lshrrev_b32_e32 v58, 3, v128
	s_add_i32 s68, 16, 0x18100
	v_lshl_add_u32 v127, v65, 1, v52
	v_xor_b32_e32 v65, v47, v128
	v_lshlrev_b32_e32 v48, 1, v48
	v_and_or_b32 v45, v45, 56, v63
	s_add_i32 s19, 16, 0x18400
	v_add_u32_e32 v120, s18, v54
	v_add_u32_e32 v57, 16, v56
	s_movk_i32 s18, 0x110
	s_movk_i32 s20, 0x90
	v_and_b32_e32 v59, 7, v128
	v_mul_u32_u24_e32 v60, 0x110, v58
	v_lshl_add_u32 v125, v58, 2, s68
	v_or_b32_e32 v58, v50, v110
	v_lshlrev_b32_e32 v65, 3, v65
	v_add_u32_e32 v66, 16, v48
	v_lshlrev_b32_e32 v45, 1, v45
	v_lshl_add_u32 v119, v128, 2, s19
	v_mad_u32_u24 v121, v53, s18, v57
	v_lshlrev_b32_e32 v61, 5, v59
	v_lshl_add_u32 v124, v59, 6, s19
	v_cmp_eq_u32_e64 s[18:19], 0, v59
	v_mad_u32_u24 v59, v58, s20, 16
	v_and_or_b32 v65, v65, 56, v63
	v_add3_u32 v133, 16, v45, v48
	v_add_u32_e32 v134, v66, v45
	v_mul_u32_u24_e32 v45, 0x110, v129
	s_mov_b32 s20, 0xd000
	v_lshlrev_b32_e32 v49, 1, v49
	v_lshlrev_b32_e32 v65, 1, v65
	v_add3_u32 v135, v52, v45, s20
	v_add_u32_e32 v45, 0x600, v128
	v_bfe_u32 v51, v128, 4, 2
	v_and_b32_e32 v49, 2, v49
	v_add3_u32 v130, 16, v65, v48
	v_add_u32_e32 v131, v66, v65
	v_mul_u32_u24_e32 v65, 0x88, v111
	v_lshrrev_b32_e32 v45, 4, v45
	v_lshlrev_b32_e32 v55, 2, v51
	v_lshl_add_u32 v132, v65, 1, v52
	v_mul_u32_u24_e32 v65, 0x110, v45
	v_lshlrev_b32_e32 v45, 4, v49
	v_or_b32_e32 v48, v45, v55
	v_or_b32_e32 v67, 2, v48
	v_add_u32_e32 v122, s62, v54
	v_mul_u32_u24_e32 v54, 0x90, v53
	s_add_i32 s30, 16, 0x15800
	v_or_b32_e32 v66, v45, v110
	v_cmp_le_u32_e64 s[22:23], v48, v53
	v_lshl_add_u32 v136, v48, 2, s42
	v_cmp_lt_u32_e64 s[24:25], v48, v53
	v_cmp_le_u32_e64 s[26:27], v67, v53
	v_lshl_add_u32 v137, v67, 2, s42
	v_or_b32_e32 v67, 3, v48
	v_lshlrev_b32_e32 v48, 1, v48
	v_or_b32_e32 v45, 16, v45
	v_add3_u32 v139, s30, v54, v48
	v_or_b32_e32 v48, v45, v55
	v_or_b32_e32 v45, v45, v110
	v_mul_u32_u24_e32 v54, 0x110, v45
	v_or_b32_e32 v45, 2, v48
	v_lshlrev_b32_e32 v51, 3, v51
	v_cmp_le_u32_e64 s[38:39], v45, v53
	v_lshl_add_u32 v141, v45, 2, s42
	v_or_b32_e32 v45, 3, v48
	v_add3_u32 v123, 16, v60, v61
	v_bitop3_b32 v60, v50, 56, v110 bitop3:0xc8
	v_cmp_le_u32_e64 s[40:41], v45, v53
	v_lshl_add_u32 v142, v45, 2, s42
	v_bitop3_b32 v45, v58, v51, 56 bitop3:0x6c
	v_lshl_add_u32 v143, v45, 1, v59
	v_bitop3_b32 v45, v51, v60, 32 bitop3:0x36
	v_or_b32_e32 v150, 16, v110
	v_lshl_add_u32 v144, v45, 1, v59
	v_lshlrev_b32_e32 v45, 2, v150
	v_or_b32_e32 v157, 32, v110
	v_add_u32_e32 v151, s43, v45
	v_add_u32_e32 v152, s62, v45
	v_add_u32_e32 v153, s68, v45
	v_add_u32_e32 v154, s54, v45
	v_add_u32_e32 v155, s65, v45
	v_add_u32_e32 v156, s64, v45
	v_lshlrev_b32_e32 v45, 2, v157
	v_or_b32_e32 v164, 48, v110
	v_mov_b32_e32 v89, 0
	v_add_u32_e32 v158, s43, v45
	v_add_u32_e32 v159, s62, v45
	v_add_u32_e32 v160, s68, v45
	v_add_u32_e32 v161, s54, v45
	v_add_u32_e32 v162, s65, v45
	v_add_u32_e32 v163, s64, v45
	v_lshlrev_b32_e32 v45, 2, v164
	v_add_u32_e32 v165, s43, v45
	v_add_u32_e32 v166, s62, v45
	v_add_u32_e32 v167, s68, v45
	v_add_u32_e32 v168, s54, v45
	v_add_u32_e32 v169, s65, v45
	v_add_u32_e32 v170, s64, v45
	v_mov_b32_e32 v45, v89
	v_mov_b32_e32 v88, v84
	v_lshl_add_u64 v[96:97], s[0:1], 0, v[44:45]
	v_mbcnt_lo_u32_b32 v44, -1, 0
	v_add_u32_e32 v62, s30, v56
	v_cmp_le_u32_e64 s[20:21], v49, v47
	v_cmp_lt_u32_e64 s[30:31], v49, v47
	v_cmp_le_u32_e64 s[34:35], v48, v53
	v_lshl_add_u32 v140, v48, 2, s42
	v_cmp_lt_u32_e64 s[36:37], v48, v53
	v_lshl_add_u64 v[48:49], s[74:75], 0, v[88:89]
	v_mov_b32_e32 v47, v89
	v_mbcnt_hi_u32_b32 v44, -1, v44
	v_lshl_add_u64 v[94:95], v[48:49], 0, v[46:47]
	v_and_b32_e32 v46, 64, v44
	v_xor_b32_e32 v45, 16, v44
	v_add_u32_e32 v47, 64, v46
	v_cmp_lt_i32_e32 vcc, v45, v47
	s_movk_i32 s16, 0x80
	v_lshl_add_u32 v61, v58, 7, v59
	v_cndmask_b32_e32 v45, v44, v45, vcc
	v_lshlrev_b32_e32 v84, 2, v45
	v_xor_b32_e32 v45, 32, v44
	v_cmp_lt_i32_e32 vcc, v45, v47
	v_or_b32_e32 v50, v55, v50
	v_lshlrev_b32_e32 v64, 2, v110
	v_cndmask_b32_e32 v45, v44, v45, vcc
	v_lshlrev_b32_e32 v171, 2, v45
	v_add_u32_e32 v45, -1, v44
	v_cmp_lt_i32_e32 vcc, v45, v46
	v_mul_u32_u24_e32 v63, 0x110, v111
	v_mul_u32_u24_e32 v66, 0x110, v66
	v_cndmask_b32_e32 v45, v45, v44, vcc
	v_lshlrev_b32_e32 v172, 2, v45
	v_add_u32_e32 v45, -2, v44
	v_cmp_lt_i32_e32 vcc, v45, v46
	v_cmp_le_u32_e64 s[28:29], v67, v53
	v_mul_u32_u24_e32 v51, 0x90, v110
	v_cndmask_b32_e32 v45, v45, v44, vcc
	v_lshlrev_b32_e32 v173, 2, v45
	v_add_u32_e32 v45, -4, v44
	v_cmp_lt_i32_e32 vcc, v45, v46
	v_mul_u32_u24_e32 v53, 0x110, v110
	v_mov_b32_e32 v77, v89
	v_cndmask_b32_e32 v45, v45, v44, vcc
	v_lshlrev_b32_e32 v174, 2, v45
	v_add_u32_e32 v45, -8, v44
	v_cmp_lt_i32_e32 vcc, v45, v46
	s_mov_b32 s55, 0
	v_cmp_gt_u32_e64 s[16:17], s16, v128
	v_cndmask_b32_e32 v45, v45, v44, vcc
	v_lshlrev_b32_e32 v175, 2, v45
	v_add_u32_e32 v45, -16, v44
	v_cmp_lt_i32_e32 vcc, v45, v46
	v_add_u32_e32 v126, s64, v64
	v_lshl_add_u32 v138, v67, 2, s42
	v_cndmask_b32_e32 v45, v45, v44, vcc
	v_lshlrev_b32_e32 v176, 2, v45
	v_subrev_u32_e32 v45, 32, v44
	v_cmp_lt_i32_e32 vcc, v45, v46
	s_and_b64 s[56:57], s[12:13], s[20:21]
	s_and_b64 s[60:61], s[12:13], s[30:31]
	v_cndmask_b32_e32 v45, v45, v44, vcc
	v_lshlrev_b32_e32 v177, 2, v45
	v_xor_b32_e32 v45, 1, v44
	v_cmp_lt_i32_e32 vcc, v45, v47
	v_add_u32_e32 v145, s43, v64
	v_add_u32_e32 v146, s62, v64
	v_cndmask_b32_e32 v45, v44, v45, vcc
	v_lshlrev_b32_e32 v178, 2, v45
	v_xor_b32_e32 v45, 2, v44
	v_cmp_lt_i32_e32 vcc, v45, v47
	v_add_u32_e32 v147, s68, v64
	v_add_u32_e32 v148, s54, v64
	v_cndmask_b32_e32 v45, v44, v45, vcc
	v_lshlrev_b32_e32 v179, 2, v45
	v_xor_b32_e32 v45, 4, v44
	v_cmp_lt_i32_e32 vcc, v45, v47
	v_add_u32_e32 v149, s65, v64
	v_lshl_add_u64 v[92:93], s[78:79], 0, v[76:77]
	v_cndmask_b32_e32 v44, v44, v45, vcc
	v_lshlrev_b32_e32 v180, 2, v44
	s_lshl_b32 s68, s84, 3
	s_lshl_b32 s69, s100, 6
	s_lshl_b32 s70, s84, 6
	v_add_u32_e32 v181, v52, v63
	v_add_u32_e32 v182, v52, v65
	s_movk_i32 s71, 0x3800
	s_movk_i32 s72, 0x1000
	s_movk_i32 s73, 0x2000
	s_movk_i32 s74, 0x4000
	s_movk_i32 s75, 0x3000
	v_add_u32_e32 v183, v57, v66
	v_add_u32_e32 v184, v57, v54
	v_add_u32_e32 v185, v61, v56
	s_brev_b32 s62, 60
	s_mov_b32 s82, 0x800000
	v_lshlrev_b32_e32 v88, 1, v50
	s_brev_b32 s83, 36
	v_add_u32_e32 v186, v62, v51
	v_add_u32_e32 v187, v57, v53
	s_mov_b32 s87, s100
	s_mov_b64 s[98:99], 0
	v_mov_b32_e32 v214, v79
	v_mov_b32_e32 v215, v75
	s_branch .LBB0_571
.LBB0_570:
	s_or_b64 exec, exec, s[0:1]
	s_waitcnt lgkmcnt(0)
	s_barrier
	ds_read_b32 v49, v126
	ds_read_b32 v48, v149
	ds_read_b32 v51, v156
	ds_read_b32 v53, v163
	ds_read_b32 v55, v170
	ds_read_b32 v54, v169
	ds_read_b32 v52, v162
	ds_read_b32 v50, v155
	s_waitcnt lgkmcnt(6)
	v_pk_mul_f32 v[48:49], v[48:49], s[62:63] op_sel_hi:[1,0]
	s_and_b32 s0, s63, 0xffffc000
	v_fma_f32 v48, -v49, v49, v48
	v_max_f32_e32 v48, 0, v48
	v_add_f32_e32 v48, 0x3727c5ac, v48
	v_mul_f32_e32 v60, 0x4b800000, v48
	v_cmp_gt_f32_e32 vcc, s82, v48
	v_sub_f32_e32 v61, v196, v49
	s_and_b32 s1, s69, 0x3fc0
	v_cndmask_b32_e32 v48, v48, v60, vcc
	v_rsq_f32_e32 v48, v48
	s_or_b32 s42, s0, s1
	v_and_b32_e32 v64, 0xffff0000, v100
	v_mul_f32_e32 v64, 0xbfb8aa3b, v64
	v_mul_f32_e32 v60, 0x45800000, v48
	v_cndmask_b32_e32 v48, v48, v60, vcc
	v_lshlrev_b32_e32 v60, 16, v100
	v_mul_f32_e32 v60, 0xbfb8aa3b, v60
	v_exp_f32_e32 v60, v60
	v_mul_f32_e32 v61, v61, v48
	v_mul_f32_e32 v61, v24, v61
	v_exp_f32_e32 v64, v64
	v_add_f32_e32 v60, 1.0, v60
	v_div_scale_f32 v62, s[0:1], v60, v60, v61
	v_rcp_f32_e32 v63, v62
	v_add_f32_e32 v64, 1.0, v64
	v_lshlrev_b32_e32 v65, 16, v101
	v_and_b32_e32 v66, 0xffff0000, v101
	v_fma_f32 v67, -v62, v63, 1.0
	v_fmac_f32_e32 v63, v67, v63
	v_div_scale_f32 v67, vcc, v61, v60, v61
	v_mul_f32_e32 v68, v67, v63
	v_fma_f32 v69, -v62, v68, v67
	v_fmac_f32_e32 v68, v69, v63
	v_fma_f32 v62, -v62, v68, v67
	v_sub_f32_e32 v67, v194, v49
	v_mul_f32_e32 v67, v67, v48
	v_mul_f32_e32 v67, v25, v67
	v_div_scale_f32 v69, s[0:1], v64, v64, v67
	v_rcp_f32_e32 v70, v69
	v_div_fmas_f32 v62, v62, v63, v68
	v_div_fixup_f32 v60, v62, v60, v61
	v_mul_f32_e32 v66, 0xbfb8aa3b, v66
	v_fma_f32 v61, -v69, v70, 1.0
	v_fmac_f32_e32 v70, v61, v70
	v_div_scale_f32 v61, vcc, v67, v64, v67
	v_mul_f32_e32 v62, v61, v70
	v_fma_f32 v63, -v69, v62, v61
	v_fmac_f32_e32 v62, v63, v70
	v_mul_f32_e32 v63, 0xbfb8aa3b, v65
	v_exp_f32_e32 v63, v63
	v_sub_f32_e32 v65, v192, v49
	v_mul_f32_e32 v65, v65, v48
	v_mul_f32_e32 v65, v26, v65
	v_add_f32_e32 v63, 1.0, v63
	v_div_scale_f32 v68, s[0:1], v63, v63, v65
	v_fma_f32 v61, -v69, v62, v61
	v_rcp_f32_e32 v69, v68
	v_exp_f32_e32 v66, v66
	v_div_fmas_f32 v61, v61, v70, v62
	v_sub_f32_e32 v49, v190, v49
	v_fma_f32 v62, -v68, v69, 1.0
	v_fmac_f32_e32 v69, v62, v69
	v_div_scale_f32 v62, vcc, v65, v63, v65
	v_mul_f32_e32 v48, v49, v48
	v_div_fixup_f32 v61, v61, v64, v67
	v_mul_f32_e32 v64, v62, v69
	v_mul_f32_e32 v48, v27, v48
	v_add_f32_e32 v49, 1.0, v66
	v_fma_f32 v67, -v68, v64, v62
	v_div_scale_f32 v66, s[0:1], v49, v49, v48
	v_fmac_f32_e32 v64, v67, v69
	v_rcp_f32_e32 v67, v66
	v_fma_f32 v62, -v68, v64, v62
	v_div_fmas_f32 v62, v62, v69, v64
	v_div_fixup_f32 v62, v62, v63, v65
	v_fma_f32 v63, -v66, v67, 1.0
	v_fmac_f32_e32 v67, v63, v67
	v_div_scale_f32 v63, vcc, v48, v49, v48
	v_mul_f32_e32 v64, v63, v67
	v_fma_f32 v65, -v66, v64, v63
	v_fmac_f32_e32 v64, v65, v67
	v_fma_f32 v63, -v66, v64, v63
	v_div_fmas_f32 v63, v63, v67, v64
	v_div_fixup_f32 v49, v63, v49, v48
	v_cvt_pk_bf16_f32 v48, v60, v61
	v_or_b32_e32 v60, s42, v110
	v_ashrrev_i32_e32 v61, 31, v60
	s_waitcnt lgkmcnt(0)
	v_pk_mul_f32 v[50:51], v[50:51], s[62:63] op_sel_hi:[1,0]
	v_lshlrev_b64 v[60:61], 12, v[60:61]
	v_fma_f32 v50, -v51, v51, v50
	v_lshl_add_u64 v[60:61], s[80:81], 0, v[60:61]
	s_and_b32 s54, s87, 0x700
	v_max_f32_e32 v50, 0, v50
	v_lshl_add_u64 v[60:61], v[60:61], 0, s[54:55]
	v_add_f32_e32 v50, 0x3727c5ac, v50
	v_cvt_pk_bf16_f32 v49, v62, v49
	v_lshl_add_u64 v[60:61], v[60:61], 0, v[88:89]
	v_mul_f32_e32 v62, 0x4b800000, v50
	v_cmp_gt_f32_e32 vcc, s82, v50
	v_add_co_u32_e64 v60, s[0:1], s83, v60
	s_nop 0
	v_cndmask_b32_e32 v50, v50, v62, vcc
	v_rsq_f32_e32 v50, v50
	v_addc_co_u32_e64 v61, s[0:1], 0, v61, s[0:1]
	global_store_dwordx2 v[60:61], v[48:49], off offset:2048
	v_lshlrev_b32_e32 v49, 16, v98
	v_mul_f32_e32 v49, 0xbfb8aa3b, v49
	v_exp_f32_e32 v49, v49
	v_mul_f32_e32 v48, 0x45800000, v50
	v_cndmask_b32_e32 v48, v50, v48, vcc
	v_sub_f32_e32 v50, v195, v51
	v_mul_f32_e32 v50, v50, v48
	v_mul_f32_e32 v50, v24, v50
	v_add_f32_e32 v49, 1.0, v49
	v_div_scale_f32 v60, s[0:1], v49, v49, v50
	v_rcp_f32_e32 v61, v60
	v_and_b32_e32 v62, 0xffff0000, v98
	v_mul_f32_e32 v62, 0xbfb8aa3b, v62
	v_exp_f32_e32 v62, v62
	v_fma_f32 v65, -v60, v61, 1.0
	v_fmac_f32_e32 v61, v65, v61
	v_div_scale_f32 v65, vcc, v50, v49, v50
	v_mul_f32_e32 v66, v65, v61
	v_fma_f32 v67, -v60, v66, v65
	v_fmac_f32_e32 v66, v67, v61
	v_fma_f32 v60, -v60, v66, v65
	v_sub_f32_e32 v65, v191, v51
	v_mul_f32_e32 v65, v65, v48
	v_mul_f32_e32 v65, v25, v65
	v_add_f32_e32 v62, 1.0, v62
	v_div_scale_f32 v67, s[0:1], v62, v62, v65
	v_rcp_f32_e32 v68, v67
	v_div_fmas_f32 v60, v60, v61, v66
	v_div_fixup_f32 v49, v60, v49, v50
	v_lshlrev_b32_e32 v63, 16, v99
	v_fma_f32 v50, -v67, v68, 1.0
	v_fmac_f32_e32 v68, v50, v68
	v_div_scale_f32 v50, vcc, v65, v62, v65
	v_mul_f32_e32 v60, v50, v68
	v_fma_f32 v61, -v67, v60, v50
	v_fmac_f32_e32 v60, v61, v68
	v_mul_f32_e32 v61, 0xbfb8aa3b, v63
	v_exp_f32_e32 v61, v61
	v_sub_f32_e32 v63, v188, v51
	v_mul_f32_e32 v63, v63, v48
	v_mul_f32_e32 v63, v26, v63
	v_add_f32_e32 v61, 1.0, v61
	v_div_scale_f32 v66, s[0:1], v61, v61, v63
	v_and_b32_e32 v64, 0xffff0000, v99
	v_fma_f32 v50, -v67, v60, v50
	v_rcp_f32_e32 v67, v66
	v_mul_f32_e32 v64, 0xbfb8aa3b, v64
	v_exp_f32_e32 v64, v64
	v_div_fmas_f32 v50, v50, v68, v60
	v_fma_f32 v60, -v66, v67, 1.0
	v_sub_f32_e32 v51, v81, v51
	v_fmac_f32_e32 v67, v60, v67
	v_div_scale_f32 v60, vcc, v63, v61, v63
	v_mul_f32_e32 v48, v51, v48
	v_div_fixup_f32 v50, v50, v62, v65
	v_mul_f32_e32 v62, v60, v67
	v_mul_f32_e32 v48, v27, v48
	v_add_f32_e32 v51, 1.0, v64
	v_fma_f32 v65, -v66, v62, v60
	v_div_scale_f32 v64, s[0:1], v51, v51, v48
	v_fmac_f32_e32 v62, v65, v67
	v_rcp_f32_e32 v65, v64
	v_fma_f32 v60, -v66, v62, v60
	v_div_fmas_f32 v60, v60, v67, v62
	v_div_fixup_f32 v60, v60, v61, v63
	v_fma_f32 v61, -v64, v65, 1.0
	v_fmac_f32_e32 v65, v61, v65
	v_div_scale_f32 v61, vcc, v48, v51, v48
	v_mul_f32_e32 v62, v61, v65
	v_fma_f32 v63, -v64, v62, v61
	v_fmac_f32_e32 v62, v63, v65
	v_fma_f32 v61, -v64, v62, v61
	v_div_fmas_f32 v61, v61, v65, v62
	v_div_fixup_f32 v51, v61, v51, v48
	v_cvt_pk_bf16_f32 v48, v49, v50
	v_or_b32_e32 v50, s42, v150
	v_cvt_pk_bf16_f32 v49, v60, v51
	v_ashrrev_i32_e32 v51, 31, v50
	v_pk_mul_f32 v[52:53], v[52:53], s[62:63] op_sel_hi:[1,0]
	v_lshlrev_b64 v[50:51], 12, v[50:51]
	v_fma_f32 v52, -v53, v53, v52
	v_lshl_add_u64 v[50:51], s[80:81], 0, v[50:51]
	v_max_f32_e32 v52, 0, v52
	v_lshl_add_u64 v[50:51], v[50:51], 0, s[54:55]
	v_add_f32_e32 v52, 0x3727c5ac, v52
	v_lshl_add_u64 v[50:51], v[50:51], 0, v[88:89]
	v_mul_f32_e32 v60, 0x4b800000, v52
	v_cmp_gt_f32_e32 vcc, s82, v52
	v_add_co_u32_e64 v50, s[0:1], s83, v50
	s_nop 0
	v_cndmask_b32_e32 v52, v52, v60, vcc
	v_rsq_f32_e32 v52, v52
	v_addc_co_u32_e64 v51, s[0:1], 0, v51, s[0:1]
	global_store_dwordx2 v[50:51], v[48:49], off offset:2048
	v_lshlrev_b32_e32 v49, 16, v90
	v_mul_f32_e32 v49, 0xbfb8aa3b, v49
	v_exp_f32_e32 v49, v49
	v_mul_f32_e32 v48, 0x45800000, v52
	v_cndmask_b32_e32 v48, v52, v48, vcc
	v_sub_f32_e32 v50, v193, v53
	v_mul_f32_e32 v50, v50, v48
	v_mul_f32_e32 v50, v24, v50
	v_add_f32_e32 v49, 1.0, v49
	v_div_scale_f32 v51, s[0:1], v49, v49, v50
	v_rcp_f32_e32 v52, v51
	v_and_b32_e32 v60, 0xffff0000, v90
	v_mul_f32_e32 v60, 0xbfb8aa3b, v60
	v_exp_f32_e32 v60, v60
	v_fma_f32 v63, -v51, v52, 1.0
	v_fmac_f32_e32 v52, v63, v52
	v_div_scale_f32 v63, vcc, v50, v49, v50
	v_mul_f32_e32 v64, v63, v52
	v_fma_f32 v65, -v51, v64, v63
	v_fmac_f32_e32 v64, v65, v52
	v_fma_f32 v51, -v51, v64, v63
	v_sub_f32_e32 v63, v189, v53
	v_mul_f32_e32 v63, v63, v48
	v_mul_f32_e32 v63, v25, v63
	v_add_f32_e32 v60, 1.0, v60
	v_div_scale_f32 v65, s[0:1], v60, v60, v63
	v_rcp_f32_e32 v66, v65
	v_div_fmas_f32 v51, v51, v52, v64
	v_div_fixup_f32 v49, v51, v49, v50
	v_lshlrev_b32_e32 v61, 16, v91
	v_fma_f32 v50, -v65, v66, 1.0
	v_fmac_f32_e32 v66, v50, v66
	v_div_scale_f32 v50, vcc, v63, v60, v63
	v_mul_f32_e32 v51, v50, v66
	v_fma_f32 v52, -v65, v51, v50
	v_fmac_f32_e32 v51, v52, v66
	v_mul_f32_e32 v52, 0xbfb8aa3b, v61
	v_exp_f32_e32 v52, v52
	v_sub_f32_e32 v61, v83, v53
	v_mul_f32_e32 v61, v61, v48
	v_mul_f32_e32 v61, v26, v61
	v_add_f32_e32 v52, 1.0, v52
	v_div_scale_f32 v64, s[0:1], v52, v52, v61
	v_and_b32_e32 v62, 0xffff0000, v91
	v_fma_f32 v50, -v65, v51, v50
	v_rcp_f32_e32 v65, v64
	v_mul_f32_e32 v62, 0xbfb8aa3b, v62
	v_exp_f32_e32 v62, v62
	v_div_fmas_f32 v50, v50, v66, v51
	v_fma_f32 v51, -v64, v65, 1.0
	v_sub_f32_e32 v53, v77, v53
	v_fmac_f32_e32 v65, v51, v65
	v_div_scale_f32 v51, vcc, v61, v52, v61
	v_mul_f32_e32 v48, v53, v48
	v_div_fixup_f32 v50, v50, v60, v63
	v_mul_f32_e32 v60, v51, v65
	v_mul_f32_e32 v48, v27, v48
	v_add_f32_e32 v53, 1.0, v62
	v_fma_f32 v63, -v64, v60, v51
	v_div_scale_f32 v62, s[0:1], v53, v53, v48
	v_fmac_f32_e32 v60, v63, v65
	v_rcp_f32_e32 v63, v62
	v_fma_f32 v51, -v64, v60, v51
	v_div_fmas_f32 v51, v51, v65, v60
	v_div_fixup_f32 v51, v51, v52, v61
	v_fma_f32 v52, -v62, v63, 1.0
	v_fmac_f32_e32 v63, v52, v63
	v_div_scale_f32 v52, vcc, v48, v53, v48
	v_mul_f32_e32 v60, v52, v63
	v_fma_f32 v61, -v62, v60, v52
	v_fmac_f32_e32 v60, v61, v63
	v_fma_f32 v52, -v62, v60, v52
	v_div_fmas_f32 v52, v52, v63, v60
	v_div_fixup_f32 v52, v52, v53, v48
	v_cvt_pk_bf16_f32 v48, v49, v50
	v_or_b32_e32 v50, s42, v157
	v_cvt_pk_bf16_f32 v49, v51, v52
	v_ashrrev_i32_e32 v51, 31, v50
	v_pk_mul_f32 v[52:53], v[54:55], s[62:63] op_sel_hi:[1,0]
	v_lshlrev_b64 v[50:51], 12, v[50:51]
	v_fma_f32 v52, -v53, v53, v52
	v_lshl_add_u64 v[50:51], s[80:81], 0, v[50:51]
	v_max_f32_e32 v52, 0, v52
	v_lshl_add_u64 v[50:51], v[50:51], 0, s[54:55]
	v_add_f32_e32 v52, 0x3727c5ac, v52
	v_lshl_add_u64 v[50:51], v[50:51], 0, v[88:89]
	v_mul_f32_e32 v54, 0x4b800000, v52
	v_cmp_gt_f32_e32 vcc, s82, v52
	v_add_co_u32_e64 v50, s[0:1], s83, v50
	s_nop 0
	v_cndmask_b32_e32 v52, v52, v54, vcc
	v_rsq_f32_e32 v52, v52
	v_addc_co_u32_e64 v51, s[0:1], 0, v51, s[0:1]
	global_store_dwordx2 v[50:51], v[48:49], off offset:2048
	v_lshlrev_b32_e32 v49, 16, v86
	v_mul_f32_e32 v49, 0xbfb8aa3b, v49
	v_exp_f32_e32 v49, v49
	v_mul_f32_e32 v48, 0x45800000, v52
	v_cndmask_b32_e32 v48, v52, v48, vcc
	v_sub_f32_e32 v50, v59, v53
	v_mul_f32_e32 v50, v50, v48
	v_mul_f32_e32 v24, v24, v50
	v_add_f32_e32 v49, 1.0, v49
	v_div_scale_f32 v50, s[0:1], v49, v49, v24
	v_rcp_f32_e32 v51, v50
	v_and_b32_e32 v52, 0xffff0000, v86
	v_mul_f32_e32 v52, 0xbfb8aa3b, v52
	v_exp_f32_e32 v52, v52
	v_fma_f32 v59, -v50, v51, 1.0
	v_fmac_f32_e32 v51, v59, v51
	v_div_scale_f32 v59, vcc, v24, v49, v24
	v_sub_f32_e32 v58, v58, v53
	v_mul_f32_e32 v60, v59, v51
	v_mul_f32_e32 v58, v58, v48
	v_fma_f32 v61, -v50, v60, v59
	v_mul_f32_e32 v25, v25, v58
	v_add_f32_e32 v52, 1.0, v52
	v_fmac_f32_e32 v60, v61, v51
	v_div_scale_f32 v58, s[0:1], v52, v52, v25
	v_fma_f32 v50, -v50, v60, v59
	v_rcp_f32_e32 v59, v58
	v_div_fmas_f32 v50, v50, v51, v60
	v_div_fixup_f32 v24, v50, v49, v24
	v_lshlrev_b32_e32 v54, 16, v87
	v_fma_f32 v49, -v58, v59, 1.0
	v_fmac_f32_e32 v59, v49, v59
	v_div_scale_f32 v49, vcc, v25, v52, v25
	v_mul_f32_e32 v50, v49, v59
	v_fma_f32 v51, -v58, v50, v49
	v_fmac_f32_e32 v50, v51, v59
	v_mul_f32_e32 v51, 0xbfb8aa3b, v54
	v_exp_f32_e32 v51, v51
	v_sub_f32_e32 v54, v57, v53
	v_mul_f32_e32 v54, v54, v48
	v_mul_f32_e32 v26, v26, v54
	v_add_f32_e32 v51, 1.0, v51
	v_div_scale_f32 v54, s[0:1], v51, v51, v26
	v_rcp_f32_e32 v57, v54
	v_fma_f32 v49, -v58, v50, v49
	v_div_fmas_f32 v49, v49, v59, v50
	v_div_fixup_f32 v25, v49, v52, v25
	v_fma_f32 v49, -v54, v57, 1.0
	v_fmac_f32_e32 v57, v49, v57
	v_div_scale_f32 v49, vcc, v26, v51, v26
	v_mul_f32_e32 v50, v49, v57
	v_and_b32_e32 v55, 0xffff0000, v87
	v_fma_f32 v52, -v54, v50, v49
	v_fmac_f32_e32 v50, v52, v57
	v_mul_f32_e32 v52, 0xbfb8aa3b, v55
	v_exp_f32_e32 v52, v52
	v_sub_f32_e32 v53, v56, v53
	v_mul_f32_e32 v48, v53, v48
	v_mul_f32_e32 v27, v27, v48
	v_add_f32_e32 v48, 1.0, v52
	v_div_scale_f32 v52, s[0:1], v48, v48, v27
	v_rcp_f32_e32 v53, v52
	v_fma_f32 v49, -v54, v50, v49
	v_div_fmas_f32 v49, v49, v57, v50
	v_div_fixup_f32 v26, v49, v51, v26
	v_fma_f32 v49, -v52, v53, 1.0
	v_fmac_f32_e32 v53, v49, v53
	v_div_scale_f32 v49, vcc, v27, v48, v27
	v_mul_f32_e32 v50, v49, v53
	v_fma_f32 v51, -v52, v50, v49
	v_fmac_f32_e32 v50, v51, v53
	v_fma_f32 v49, -v52, v50, v49
	v_div_fmas_f32 v49, v49, v53, v50
	v_div_fixup_f32 v27, v49, v48, v27
	v_cvt_pk_bf16_f32 v24, v24, v25
	v_cvt_pk_bf16_f32 v25, v26, v27
	v_or_b32_e32 v26, s42, v164
	v_ashrrev_i32_e32 v27, 31, v26
	v_lshlrev_b64 v[26:27], 12, v[26:27]
	v_lshl_add_u64 v[26:27], s[80:81], 0, v[26:27]
	v_lshl_add_u64 v[26:27], v[26:27], 0, s[54:55]
	v_lshl_add_u64 v[26:27], v[26:27], 0, v[88:89]
	v_add_co_u32_e32 v26, vcc, 0x24000000, v26
	s_lshl_b32 s63, s86, 3
	s_nop 0
	v_addc_co_u32_e32 v27, vcc, 0, v27, vcc
	global_store_dwordx2 v[26:27], v[24:25], off offset:2048
	s_waitcnt vmcnt(4)
	v_mov_b64_e32 v[24:25], v[44:45]
	s_lshl_b32 s69, s86, 6
	s_andn2_b64 vcc, exec, s[64:65]
	v_mov_b64_e32 v[100:101], v[102:103]
	v_mov_b64_e32 v[98:99], v[104:105]
	v_mov_b64_e32 v[90:91], v[106:107]
	v_mov_b64_e32 v[86:87], v[108:109]
	s_mov_b32 s87, s86
	v_mov_b64_e32 v[26:27], v[46:47]
	s_barrier
	s_cbranch_vccz .LBB0_613

.LBB0_573:
	s_or_b64 exec, exec, s[0:1]
	ds_write_b128 v127, v[0:3]
	ds_write_b128 v127, v[4:7] offset:17408
	ds_write_b16 v130, v8 offset:34816
	ds_write_b16_d16_hi v131, v8 offset:34960
	ds_write_b16 v130, v9 offset:35104
	ds_write_b16_d16_hi v131, v9 offset:35248
	ds_write_b16 v130, v10 offset:35392
	ds_write_b16_d16_hi v131, v10 offset:35536
	ds_write_b16 v130, v11 offset:35680
	ds_write_b16_d16_hi v131, v11 offset:35824
	ds_write_b128 v132, v[12:15]
	ds_write_b128 v132, v[16:19] offset:17408
	ds_write_b16 v133, v20 offset:34816
	ds_write_b16_d16_hi v134, v20 offset:34960
	ds_write_b16 v133, v21 offset:35104
	ds_write_b16_d16_hi v134, v21 offset:35248
	ds_write_b16 v133, v22 offset:35392
	ds_write_b16_d16_hi v134, v22 offset:35536
	ds_write_b16 v133, v23 offset:35680
	ds_write_b16_d16_hi v134, v23 offset:35824
	ds_write_b128 v135, v[28:31]
	ds_write_b128 v181, v[32:35] offset:53248
	ds_write_b128 v135, v[36:39] offset:17408
	ds_write_b128 v182, v[40:43] offset:53248
	s_and_saveexec_b64 s[0:1], s[16:17]
	ds_write_b32 v119, v75
	s_or_b64 exec, exec, s[0:1]
	s_add_i32 s86, s87, 1
	s_and_b32 s101, s86, 7
	s_cmp_eq_u32 s101, 0
	s_cselect_b32 s101, 0x7f8, 0
	s_add_i32 s86, s86, s101
	s_cmpk_gt_i32 s86, 0xfff
	s_cselect_b64 s[64:65], -1, 0
	s_waitcnt vmcnt(0)
	v_mov_b64_e32 v[46:47], v[26:27]
	s_and_b64 vcc, exec, s[64:65]
	v_mov_b64_e32 v[102:103], v[100:101]
	v_mov_b64_e32 v[104:105], v[98:99]
	v_mov_b64_e32 v[106:107], v[90:91]
	v_mov_b64_e32 v[108:109], v[86:87]
	v_mov_b64_e32 v[44:45], v[24:25]
	s_waitcnt lgkmcnt(0)
	s_barrier
	s_cbranch_vccnz .LBB0_579
	s_and_b32 s43, s86, 0xff
	s_lshl_b32 s0, s86, 3
	s_and_b32 s0, s0, 0xffffc000
	s_lshl_b32 s1, s43, 6
	s_or_b32 s89, s0, s1
	s_bfe_u32 s88, s86, 0x30008
	v_or_b32_e32 v0, s89, v129
	v_mov_b64_e32 v[44:45], s[52:53]
	v_mad_i64_i32 v[0:1], s[0:1], v0, s71, v[44:45]
	s_lshl_b32 s54, s88, 8
	v_mov_b32_e32 v77, v89
	v_lshl_add_u64 v[0:1], v[0:1], 0, s[54:55]
	v_add_u32_e32 v10, s89, v111
	v_lshl_add_u64 v[0:1], v[0:1], 0, v[76:77]
	v_mad_i64_i32 v[10:11], s[0:1], v10, s71, v[44:45]
	s_cmp_lg_u32 s43, 0
	v_add_co_u32_e32 v2, vcc, s72, v0
	s_cselect_b64 s[0:1], -1, 0
	s_nop 0
	v_addc_co_u32_e32 v3, vcc, 0, v1, vcc
	s_cmp_lg_u64 s[0:1], 0
	v_add_co_u32_e32 v8, vcc, s73, v0
	v_lshl_add_u64 v[10:11], v[10:11], 0, s[54:55]
	s_subb_u32 s42, s86, 0
	v_addc_co_u32_e32 v9, vcc, 0, v1, vcc
	v_lshl_add_u64 v[16:17], v[10:11], 0, v[76:77]
	s_cmp_eq_u32 s43, 0
	v_add_co_u32_e32 v12, vcc, s72, v16
	s_cselect_b64 s[0:1], -1, 0
	s_ashr_i32 s43, s42, 31
	v_addc_co_u32_e32 v13, vcc, 0, v17, vcc
	s_lshl_b64 s[90:91], s[42:43], 15
	v_add_co_u32_e32 v20, vcc, s73, v16
	v_lshl_add_u64 v[36:37], v[92:93], 0, s[90:91]
	v_mov_b32_e32 v81, v89
	v_mov_b32_e32 v83, v89
	v_addc_co_u32_e32 v21, vcc, 0, v17, vcc
	v_lshl_add_u64 v[38:39], v[36:37], 0, v[80:81]
	v_lshl_add_u64 v[32:33], v[36:37], 0, v[82:83]
	s_lshl_b64 s[90:91], s[42:43], 9
	s_lshl_b64 s[42:43], s[42:43], 2
	global_load_dwordx4 v[0:3], v[2:3], off offset:2048
	s_nop 0
	global_load_dwordx4 v[4:7], v[8:9], off
	s_nop 0
	global_load_dwordx4 v[8:11], v[8:9], off offset:2048
	s_nop 0
	global_load_dwordx4 v[12:15], v[12:13], off offset:2048
	s_nop 0
	global_load_dwordx4 v[16:19], v[20:21], off
	s_nop 0
	global_load_dwordx4 v[20:23], v[20:21], off offset:2048
	s_nop 0
	global_load_dwordx4 v[28:31], v[38:39], off
	s_nop 0
	global_load_dwordx4 v[32:35], v[32:33], off
	v_add_co_u32_e32 v38, vcc, s74, v38
	v_mov_b32_e32 v79, v89
	s_add_u32 s42, s66, s42
	v_addc_co_u32_e32 v39, vcc, 0, v39, vcc
	v_lshl_add_u64 v[40:41], v[36:37], 0, v[78:79]
	s_addc_u32 s43, s67, s43
	v_or_b32_e32 v56, s89, v110
	global_load_dwordx4 v[36:39], v[38:39], off
	s_nop 0
	global_load_dwordx4 v[40:43], v[40:41], off
	v_mov_b32_e32 v73, v89
	global_load_dword v214, v89, s[42:43]
	v_mad_i64_i32 v[50:51], s[42:43], v56, s71, v[44:45]
	v_lshl_add_u64 v[50:51], v[50:51], 0, s[54:55]
	v_or_b32_e32 v49, 16, v56
	v_lshl_add_u64 v[50:51], v[50:51], 0, v[72:73]
	v_mov_b32_e32 v75, v89
	v_mad_i64_i32 v[52:53], s[42:43], v49, s71, v[44:45]
	v_lshl_add_u64 v[50:51], v[50:51], 0, v[74:75]
	v_lshl_add_u64 v[52:53], v[52:53], 0, s[54:55]
	v_or_b32_e32 v49, 32, v56
	v_add_co_u32_e32 v50, vcc, s75, v50
	v_lshl_add_u64 v[52:53], v[52:53], 0, v[72:73]
	v_mad_i64_i32 v[54:55], s[42:43], v49, s71, v[44:45]
	v_addc_co_u32_e32 v51, vcc, 0, v51, vcc
	v_lshl_add_u64 v[52:53], v[52:53], 0, v[74:75]
	v_lshl_add_u64 v[54:55], v[54:55], 0, s[54:55]
	v_add_co_u32_e32 v52, vcc, s75, v52
	v_lshl_add_u64 v[54:55], v[54:55], 0, v[72:73]
	s_nop 0
	v_addc_co_u32_e32 v53, vcc, 0, v53, vcc
	v_lshl_add_u64 v[54:55], v[54:55], 0, v[74:75]
	v_lshl_add_u64 v[46:47], v[96:97], 0, s[90:91]
	v_add_co_u32_e32 v54, vcc, s75, v54
	v_mov_b32_e32 v85, 0
	s_nop 0
	v_addc_co_u32_e32 v55, vcc, 0, v55, vcc
	global_load_dword v215, v[46:47], off
	global_load_dwordx2 v[102:103], v[50:51], off
	global_load_dwordx2 v[104:105], v[52:53], off
	global_load_dwordx2 v[106:107], v[54:55], off
	v_or_b32_e32 v46, 48, v56
	v_mad_i64_i32 v[44:45], s[42:43], v46, s71, v[44:45]
	v_lshl_add_u64 v[44:45], v[44:45], 0, s[54:55]
	v_lshl_add_u64 v[44:45], v[44:45], 0, v[72:73]
	v_lshl_add_u64 v[44:45], v[44:45], 0, v[74:75]
	v_add_co_u32_e32 v44, vcc, 0x3000, v44
	s_lshl_b32 s54, s88, 9
	s_nop 0
	v_addc_co_u32_e32 v45, vcc, 0, v45, vcc
	global_load_dwordx2 v[108:109], v[44:45], off
	v_lshl_add_u64 v[44:45], v[94:95], 0, s[54:55]
	global_load_dwordx4 v[44:47], v[44:45], off
	v_mov_b32_e32 v73, 0
	s_and_saveexec_b64 s[42:43], s[2:3]
	s_cbranch_execz .LBB0_578
	v_or_b32_e32 v50, s89, v128
	v_ashrrev_i32_e32 v51, 31, v50
	v_lshlrev_b64 v[50:51], 6, v[50:51]
	v_lshl_add_u64 v[50:51], s[50:51], 0, v[50:51]
	s_lshl_b32 s54, s88, 2
	v_lshl_add_u64 v[50:51], v[50:51], 0, s[54:55]
	global_load_dword v85, v[50:51], off
	global_load_dword v73, v[50:51], off offset:32
